# v98: v93 + FoX prologue query rows via coalesced loads + wave-private swizzled LDS transpose
# baseline (speedup 1.0000x reference)
; template <int MODE>
; __device__ __forceinline__ void attn_unit(const Params& P, LAS unsigned char* lds, const int b, const int h, const int qb) {
;     ...
;     { const bf16_t* qp = Qb + (size_t)q * RS + (FOX ? 0 : 64 * mp) + 8 * hh;
; #pragma unroll
;       for (int ks = 0; ks < NQ; ++ks) Qf[ks] = *(const bf16x8*)(qp + 16 * ks); }
;     const int nt = (q0 + ROWS) / 64;
;     int kt0 = 0;
;     const float* Cl = (const float*)(P.ws + WS_C) + (size_t)(b * 8 + h) * S_;
;     if (FOX) {
;         const int kd = q0 / 64; int pred = 0;
;         if (tid < kd) pred = (tab[TAB_AQ2] + Cl[q0] - Cl[tid * 64 + 63] >= -150.0f) ? 1 : 0;
;         kt0 = kd - __syncthreads_count(pred);
; __device__ __forceinline__ void attn_phase(const Params& P, LAS unsigned char* lds) {
;     ...
;         if (tid == 0) { int u = -1;
;             for (int k = 0; k < 8; ++k) { const int qi = (xq + k) & 7; const unsigned v = atomicAdd(ctr + qi, 1u); if (v < (unsigned)QN) { u = qi * QN + (int)v; break; } }
;             misc[0] = u; }
;         __syncthreads();
;         const int u = misc[0];
;         __syncthreads();
;         if (u < 0) break;
;         const int qi = u / QN, v = u % QN;
;         if (v < 256) { const int bh = qi * 4 + (v >> 6), qb = 63 - (v & 63); if (bounded) attn_unit<1>(P, lds, bh >> 3, bh & 7, qb); else attn_unit<2>(P, lds, bh >> 3, bh & 7, qb); }
;         else { const int v2 = v - 256; const int bh = qi * 4 + (v2 >> 5), qb = 31 - (v2 & 31); attn_unit<0>(P, lds, bh >> 3, bh & 7, qb); }
.LBB0_427:
	s_or_b64 exec, exec, s[64:65]
	s_waitcnt lgkmcnt(0)
	s_barrier
	ds_read_b32 v0, v234
	s_waitcnt lgkmcnt(0)
	s_barrier
	v_cmp_gt_i32_e32 vcc, 0, v0
	v_readfirstlane_b32 s0, v0
	s_cbranch_vccnz .LBB0_460
	s_mul_hi_u32 s1, s0, 0xaaaaaaab
	s_lshr_b32 s11, s1, 8
	s_mul_i32 s1, s11, 0x180
	s_sub_i32 s10, s0, s1
	s_cmpk_gt_u32 s10, 0xff
	s_mov_b64 s[8:9], -1
	s_cbranch_scc0 .LBB0_466
	s_add_i32 s0, s10, 0xffffff00
	v_mov_b32_e32 v5, v178
	s_lshl_b32 s1, s11, 2
	s_lshr_b32 s0, s0, 5
	s_add_i32 s12, s0, s1
	v_readfirstlane_b32 s23, v5
	s_andn2_b32 s1, 31, s10
	s_ashr_i32 s22, s23, 6
	s_lshl_b32 s38, s1, 8
	s_lshl_b32 s0, s22, 5
	s_add_i32 s0, s0, s38
	v_and_or_b32 v180, v5, 31, s0
	s_lshl_b64 s[8:9], s[12:13], 21
	s_add_u32 s8, s18, s8
	v_ashrrev_i32_e32 v181, 31, v180
	v_bfe_u32 v4, v5, 5, 1
	s_addc_u32 s9, s19, s9
	v_and_b32_e32 v2, -32, v180
	v_lshlrev_b32_e32 v2, 8, v2
	v_and_b32_e32 v0, 63, v5
	v_lshl_add_u32 v2, v0, 4, v2
	v_mov_b32_e32 v3, 0
	v_lshl_add_u64 v[2:3], s[8:9], 0, v[2:3]
	v_add_co_u32_e32 v236, vcc, 0x1000, v2
	v_addc_co_u32_e32 v237, vcc, 0, v3, vcc
	global_load_dwordx4 v[130:133], v[2:3], off
	global_load_dwordx4 v[134:137], v[2:3], off offset:1024
	global_load_dwordx4 v[138:141], v[2:3], off offset:2048
	global_load_dwordx4 v[142:145], v[2:3], off offset:3072
	global_load_dwordx4 v[146:149], v[236:237], off
	global_load_dwordx4 v[150:153], v[236:237], off offset:1024
	global_load_dwordx4 v[154:157], v[236:237], off offset:2048
	global_load_dwordx4 v[158:161], v[236:237], off offset:3072
	s_lshl_b64 s[8:9], s[12:13], 15
	s_add_u32 s66, s82, s8
	s_addc_u32 s67, s83, s9
	v_lshlrev_b32_e32 v207, 2, v180
	global_load_dword v208, v207, s[66:67]
	s_lshl_b32 s33, s1, 2
	v_cmp_gt_i32_e32 vcc, s33, v5
	v_mov_b32_e32 v0, 0
	s_and_saveexec_b64 s[8:9], vcc
	s_cbranch_execz .LBB0_431
	v_lshlrev_b32_e32 v2, 6, v5
	s_lshl_b32 s1, s38, 2
	v_ashrrev_i32_e32 v3, 31, v2
	v_mov_b32_e32 v0, s1
	v_lshl_add_u64 v[2:3], v[2:3], 2, s[66:67]
	global_load_dword v6, v1, s[60:61]
	s_nop 0
	global_load_dword v0, v0, s[66:67]
	s_nop 0
	global_load_dword v2, v[2:3], off offset:252
	s_mov_b32 s1, 0xc2800000
	s_waitcnt vmcnt(1)
	v_add_f32_e32 v0, v6, v0
	s_waitcnt vmcnt(0)
	v_sub_f32_e32 v0, v0, v2
	v_cmp_le_f32_e32 vcc, s1, v0
	s_nop 1
	v_cndmask_b32_e64 v0, 0, 1, vcc

; #define ATT_WAITV(n) asm volatile("s_waitcnt vmcnt(" #n ")" ::: "memory")
; template <int MODE>
; __device__ __forceinline__ void attn_unit(const Params& P, LAS unsigned char* lds, const int b, const int h, const int qb) {
;     ...
;     { const bf16_t* qp = Qb + (size_t)q * RS + (FOX ? 0 : 64 * mp) + 8 * hh;
; #pragma unroll
;       for (int ks = 0; ks < NQ; ++ks) Qf[ks] = *(const bf16x8*)(qp + 16 * ks); }
;     ...
;     const int krow = 4 * w + (lane >> 4), kchunk = (lane & 15) ^ (krow & 15);
;     const bf16_t* kg = Kb_ + (size_t)krow * RS + kchunk * 8;
;     const int vst = 2 * w + (lane >> 5), vkey = (vst >> 2) * 8 + ((lane >> 2) & 7);
;     const bf16_t* vg = Vb_ + (size_t)vkey * RS + (vst & 3) * 32 + (lane & 3) * 8;
;     const float* cg_ = Cl + lane;
;     ...
;     const int pr = (r & 19) | ((r & 4) << 1) | ((r & 8) >> 1);
;     const unsigned kra = pr * 256, kswz = pr & 15;
;     const unsigned vra = 16384 + hh * 2048 + ((lane & 15) >> 2) * 64 + ((lane >> 4) & 1) * 32 + (lane & 3) * 8;
;     f32x16 O[4];
; #pragma unroll
;     for (int d = 0; d < 4; ++d)
; #pragma unroll
;         for (int i = 0; i < 16; ++i) O[d][i] = 0.f;
;     float m1 = ONLINE ? -INFINITY : 0.f, l1 = 0.f;
;     const int ktw_last = (q0w + 31) / 64;
;     ATT_WAITV(0); __builtin_amdgcn_s_barrier(); asm volatile("" ::: "memory");
.LBB0_438:
	s_lshl_b64 s[8:9], s[12:13], 20
	s_lshl_b64 s[64:65], s[8:9], 1
	s_add_u32 s8, s78, s64
	s_addc_u32 s9, s79, s65
	v_and_b32_e32 v3, 63, v5
	s_add_u32 s40, s80, s64
	s_addc_u32 s41, s81, s65
	s_lshl_b32 s58, s22, 2
	v_lshrrev_b32_e32 v2, 4, v3
	v_or_b32_e32 v6, s58, v2
	v_ashrrev_i32_e32 v7, 31, v6
	v_lshlrev_b64 v[6:7], 8, v[6:7]
	s_ashr_i32 s23, s23, 4
	v_lshrrev_b32_e32 v8, 2, v5
	v_bitop3_b32 v0, s58, v5, v2 bitop3:0x36
	s_lshl_b32 s58, s22, 1
	v_bfi_b32 v8, -8, s23, v8
	v_lshl_add_u64 v[6:7], s[8:9], 0, v[6:7]
	s_lshl_b32 s8, s22, 10
	v_ashrrev_i32_e32 v9, 31, v8
	v_and_or_b32 v10, s58, 2, v4
	v_lshlrev_b32_e32 v0, 4, v0
	s_add_i32 s58, s8, 0x100
	s_lshl_b32 s8, s22, 8
	s_add_i32 s1, s38, 0x100
	v_lshlrev_b64 v[8:9], 8, v[8:9]
	v_lshlrev_b32_e32 v11, 3, v5
	v_and_b32_e32 v0, 0xf0, v0
	s_add_i32 s59, s8, 0x100
	s_lshr_b32 s1, s1, 6
	v_and_b32_e32 v190, 24, v11
	s_sub_i32 s33, s33, s39
	v_lshl_add_u64 v[184:185], v[6:7], 0, v[0:1]
	v_lshl_add_u64 v[6:7], s[40:41], 0, v[8:9]
	v_lshlrev_b32_e32 v0, 6, v10
	s_add_i32 s59, s59, 0x20000
	v_lshl_add_u64 v[6:7], v[6:7], 0, v[0:1]
	v_lshlrev_b32_e32 v0, 1, v190
	s_waitcnt vmcnt(0)
	v_and_b32_e32 v238, 63, v178
	v_lshrrev_b32_e32 v239, 6, v178
	v_lshlrev_b32_e32 v239, 13, v239
	v_add_u32_e32 v239, 0x100, v239
	v_lshrrev_b32_e32 v240, 4, v238
	v_and_b32_e32 v241, 15, v238
	v_xor_b32_e32 v241, v240, v241
	v_lshlrev_b32_e32 v241, 4, v241
	v_lshl_add_u32 v240, v240, 8, v239
	v_add_u32_e32 v240, v240, v241
	v_xor_b32_e32 v241, 0x40, v240
	v_xor_b32_e32 v242, 0x80, v240
	v_xor_b32_e32 v243, 0xc0, v240
	ds_write_b128 v240, v[130:133]
	ds_write_b128 v241, v[134:137] offset:1024
	ds_write_b128 v242, v[138:141] offset:2048
	ds_write_b128 v243, v[142:145] offset:3072
	ds_write_b128 v240, v[146:149] offset:4096
	ds_write_b128 v241, v[150:153] offset:5120
	ds_write_b128 v242, v[154:157] offset:6144
	ds_write_b128 v243, v[158:161] offset:7168
	v_and_b32_e32 v244, 31, v238
	v_lshrrev_b32_e32 v245, 5, v238
	v_and_b32_e32 v246, 15, v244
	v_xor_b32_e32 v245, v245, v246
	v_lshlrev_b32_e32 v245, 4, v245
	v_lshl_add_u32 v244, v244, 8, v239
	v_add_u32_e32 v244, v244, v245
	v_xor_b32_e32 v245, 0x20, v244
	v_xor_b32_e32 v246, 0x40, v244
	v_xor_b32_e32 v247, 0x60, v244
	v_xor_b32_e32 v248, 0x80, v244
	v_xor_b32_e32 v249, 0xa0, v244
	v_xor_b32_e32 v250, 0xc0, v244
	v_xor_b32_e32 v238, 0xe0, v244
	s_waitcnt lgkmcnt(0)
	ds_read_b128 v[130:133], v244
	ds_read_b128 v[134:137], v245
	ds_read_b128 v[138:141], v246
	ds_read_b128 v[142:145], v247
	ds_read_b128 v[146:149], v248
	ds_read_b128 v[150:153], v249
	ds_read_b128 v[154:157], v250
	ds_read_b128 v[158:161], v238
	s_waitcnt lgkmcnt(0)
	v_cndmask_b32_e64 v212, 0, v208, s[100:101]
	v_mov_b32_e32 v213, v212
	v_mov_b32_e32 v214, v212
	v_mov_b32_e32 v215, v212
	v_mov_b32_e32 v216, v212
	v_mov_b32_e32 v217, v212
	v_mov_b32_e32 v218, v212
	v_mov_b32_e32 v219, v212
	v_mov_b32_e32 v220, v212
	v_mov_b32_e32 v221, v212
	v_mov_b32_e32 v222, v212
	v_mov_b32_e32 v223, v212
	v_mov_b32_e32 v224, v212
	v_mov_b32_e32 v225, v212
	v_mov_b32_e32 v226, v212
	v_mov_b32_e32 v227, v212
	v_readlane_b32 vcc_hi, v255, 8
	v_readfirstlane_b32 vcc_lo, v208
	s_nop 1
	v_mov_b32_e32 v252, vcc_hi
	v_add_f32_e32 v252, vcc_lo, v252
	v_add_f32_e32 v252, 0x42800000, v252
	v_mov_b32_e32 v251, 1
	s_barrier
	s_cmp_lt_i32 s33, s1
	v_lshl_add_u64 v[186:187], v[6:7], 0, v[0:1]
	v_lshlrev_b32_e32 v0, 2, v3
	s_cselect_b64 s[8:9], -1, 0
	v_lshlrev_b64 v[182:183], 7, v[180:181]
	v_lshlrev_b32_e32 v96, 3, v4
	v_lshl_add_u64 v[188:189], s[66:67], 0, v[0:1]
	s_and_b64 vcc, exec, s[8:9]
	s_cbranch_vccnz .LBB0_461
	s_add_i32 s22, s33, 1
	s_cmp_ge_i32 s22, s1
	s_cbranch_scc0 .LBB0_462
